# grid barrier: single-hop release (the last arriver bumps every XCD's local generation itself; XCD leaders no longer forward)
# speedup vs baseline: 1.0514x; 1.0071x over previous
.LBB0_150:
	s_or_b64 exec, exec, s[14:15]
	v_cvt_f32_u32_e32 v3, v0
	s_waitcnt vmcnt(0)
	v_readfirstlane_b32 s12, v2
	s_add_u32 s14, s30, 0x43500
	s_addc_u32 s15, s31, 0
	v_rcp_iflag_f32_e32 v3, v3
	v_add_u32_e32 v1, s12, v1
	v_add_u32_e32 v4, 1, v1
	s_mov_b64 s[16:17], -1
	v_mul_f32_e32 v2, 0x4f7ffffe, v3
	v_cvt_u32_f32_e32 v2, v2
	v_sub_u32_e32 v3, 0, v0
	v_mul_lo_u32 v3, v3, v2
	v_mul_hi_u32 v3, v2, v3
	v_add_u32_e32 v2, v2, v3
	v_mul_hi_u32 v2, v1, v2
	v_mul_lo_u32 v3, v2, v0
	v_sub_u32_e32 v1, v1, v3
	v_add_u32_e32 v5, 1, v2
	v_cmp_ge_u32_e32 vcc, v1, v0
	v_sub_u32_e32 v3, v1, v0
	s_nop 0
	v_cndmask_b32_e32 v2, v2, v5, vcc
	v_cndmask_b32_e32 v1, v1, v3, vcc
	v_add_u32_e32 v3, 1, v2
	v_cmp_ge_u32_e32 vcc, v1, v0
	s_nop 1
	v_cndmask_b32_e32 v2, v2, v3, vcc
	v_mul_lo_u32 v1, v0, v2
	v_add_u32_e32 v0, v1, v0
	v_cmp_ne_u32_e32 vcc, v4, v0
	v_mov_b64_e32 v[0:1], s[14:15]
	s_and_b64 s[98:99], exec, vcc
	s_cbranch_scc1 .Lhop_notlast_0
	v_mov_b32_e32 v16, 1
	v_mov_b32_e32 v17, 0x2400
	global_atomic_add v17, v16, s[34:35]
	v_mov_b32_e32 v17, 0x2500
	global_atomic_add v17, v16, s[34:35]
	v_mov_b32_e32 v17, 0x2600
	global_atomic_add v17, v16, s[34:35]
	v_mov_b32_e32 v17, 0x2700
	global_atomic_add v17, v16, s[34:35]
	v_mov_b32_e32 v17, 0x2800
	global_atomic_add v17, v16, s[34:35]
	v_mov_b32_e32 v17, 0x2900
	global_atomic_add v17, v16, s[34:35]
	v_mov_b32_e32 v17, 0x2a00
	global_atomic_add v17, v16, s[34:35]
	v_mov_b32_e32 v17, 0x2b00
	global_atomic_add v17, v16, s[34:35]
	v_mov_b32_e32 v17, 0x2c00
	global_atomic_add v17, v16, s[34:35]
	v_mov_b32_e32 v17, 0x2d00
	global_atomic_add v17, v16, s[34:35]
	v_mov_b32_e32 v17, 0x2e00
	global_atomic_add v17, v16, s[34:35]
	v_mov_b32_e32 v17, 0x2f00
	global_atomic_add v17, v16, s[34:35]
	v_mov_b32_e32 v17, 0x3000
	global_atomic_add v17, v16, s[34:35]
	v_mov_b32_e32 v17, 0x3100
	global_atomic_add v17, v16, s[34:35]
	v_mov_b32_e32 v17, 0x3200
	global_atomic_add v17, v16, s[34:35]
	v_mov_b32_e32 v17, 0x3300
	global_atomic_add v17, v16, s[34:35]
.Lhop_notlast_0:
	s_and_saveexec_b64 s[12:13], vcc
	s_cbranch_execz .LBB0_162
	v_mov_b32_e32 v0, 0
	global_load_dword v1, v0, s[14:15] sc1
	s_mov_b64 s[20:21], 0
	s_waitcnt vmcnt(0)
	v_cmp_eq_u32_e32 vcc, v1, v2
	s_and_saveexec_b64 s[18:19], vcc
	s_cbranch_execz .LBB0_161
	s_add_u32 s16, s30, 0x40200
	s_addc_u32 s17, s31, 0
	s_mov_b32 s40, 1
	s_branch .LBB0_154

.LBB0_164:
	s_or_b64 exec, exec, s[12:13]
	s_mov_b64 s[12:13], exec
	v_mbcnt_lo_u32_b32 v0, s12, 0
	v_mbcnt_hi_u32_b32 v0, s13, v0
	v_cmp_eq_u32_e32 vcc, 0, v0
	s_waitcnt vmcnt(0)
	buffer_inv sc1
	s_and_saveexec_b64 s[14:15], vcc
	s_cbranch_execz .LBB0_166
	s_bcnt1_i32_b64 s12, s[12:13]
	v_mov_b32_e32 v0, 0x2000
	v_mov_b32_e32 v1, s12
	s_nop 0

.LBB0_553:
	s_or_b64 exec, exec, s[12:13]
	v_cvt_f32_u32_e32 v3, v0
	s_waitcnt vmcnt(0)
	v_readfirstlane_b32 s10, v2
	s_add_u32 s12, s30, 0x43500
	s_addc_u32 s13, s31, 0
	v_rcp_iflag_f32_e32 v3, v3
	v_add_u32_e32 v1, s10, v1
	v_add_u32_e32 v4, 1, v1
	s_mov_b64 s[14:15], -1
	v_mul_f32_e32 v2, 0x4f7ffffe, v3
	v_cvt_u32_f32_e32 v2, v2
	v_sub_u32_e32 v3, 0, v0
	v_mul_lo_u32 v3, v3, v2
	v_mul_hi_u32 v3, v2, v3
	v_add_u32_e32 v2, v2, v3
	v_mul_hi_u32 v2, v1, v2
	v_mul_lo_u32 v3, v2, v0
	v_sub_u32_e32 v1, v1, v3
	v_add_u32_e32 v5, 1, v2
	v_cmp_ge_u32_e32 vcc, v1, v0
	v_sub_u32_e32 v3, v1, v0
	s_nop 0
	v_cndmask_b32_e32 v2, v2, v5, vcc
	v_cndmask_b32_e32 v1, v1, v3, vcc
	v_add_u32_e32 v3, 1, v2
	v_cmp_ge_u32_e32 vcc, v1, v0
	s_nop 1
	v_cndmask_b32_e32 v2, v2, v3, vcc
	v_mul_lo_u32 v1, v0, v2
	v_add_u32_e32 v0, v1, v0
	v_cmp_ne_u32_e32 vcc, v4, v0
	v_mov_b64_e32 v[0:1], s[12:13]
	s_and_b64 s[98:99], exec, vcc
	s_cbranch_scc1 .Lhop_notlast_2
	v_mov_b32_e32 v16, 1
	v_mov_b32_e32 v17, 0x2400
	global_atomic_add v17, v16, s[34:35]
	v_mov_b32_e32 v17, 0x2500
	global_atomic_add v17, v16, s[34:35]
	v_mov_b32_e32 v17, 0x2600
	global_atomic_add v17, v16, s[34:35]
	v_mov_b32_e32 v17, 0x2700
	global_atomic_add v17, v16, s[34:35]
	v_mov_b32_e32 v17, 0x2800
	global_atomic_add v17, v16, s[34:35]
	v_mov_b32_e32 v17, 0x2900
	global_atomic_add v17, v16, s[34:35]
	v_mov_b32_e32 v17, 0x2a00
	global_atomic_add v17, v16, s[34:35]
	v_mov_b32_e32 v17, 0x2b00
	global_atomic_add v17, v16, s[34:35]
	v_mov_b32_e32 v17, 0x2c00
	global_atomic_add v17, v16, s[34:35]
	v_mov_b32_e32 v17, 0x2d00
	global_atomic_add v17, v16, s[34:35]
	v_mov_b32_e32 v17, 0x2e00
	global_atomic_add v17, v16, s[34:35]
	v_mov_b32_e32 v17, 0x2f00
	global_atomic_add v17, v16, s[34:35]
	v_mov_b32_e32 v17, 0x3000
	global_atomic_add v17, v16, s[34:35]
	v_mov_b32_e32 v17, 0x3100
	global_atomic_add v17, v16, s[34:35]
	v_mov_b32_e32 v17, 0x3200
	global_atomic_add v17, v16, s[34:35]
	v_mov_b32_e32 v17, 0x3300
	global_atomic_add v17, v16, s[34:35]
.Lhop_notlast_2:
	s_and_saveexec_b64 s[10:11], vcc
	s_cbranch_execz .LBB0_565
	v_mov_b32_e32 v0, 0
	global_load_dword v1, v0, s[12:13] sc1
	s_mov_b64 s[18:19], 0
	s_waitcnt vmcnt(0)
	v_cmp_eq_u32_e32 vcc, v1, v2
	s_and_saveexec_b64 s[16:17], vcc
	s_cbranch_execz .LBB0_564
	s_add_u32 s14, s30, 0x40200
	s_addc_u32 s15, s31, 0
	s_mov_b32 s38, 1
	s_branch .LBB0_557

.LBB0_567:
	s_or_b64 exec, exec, s[10:11]
	s_mov_b64 s[10:11], exec
	v_mbcnt_lo_u32_b32 v0, s10, 0
	v_mbcnt_hi_u32_b32 v0, s11, v0
	v_cmp_eq_u32_e32 vcc, 0, v0
	s_waitcnt vmcnt(0)
	buffer_inv sc1
	s_and_saveexec_b64 s[12:13], vcc
	s_cbranch_execz .LBB0_569
	s_bcnt1_i32_b64 s10, s[10:11]
	v_mov_b32_e32 v0, 0x2000
	v_mov_b32_e32 v1, s10
	s_nop 0

.Lhop_notlast_11:
	s_and_saveexec_b64 s[10:11], vcc
	s_cbranch_execz .LBB0_1377
	v_mov_b32_e32 v0, 0
	global_load_dword v1, v0, s[12:13] sc1
	s_mov_b64 s[18:19], 0
	s_waitcnt vmcnt(0)
	v_cmp_eq_u32_e32 vcc, v1, v2
	s_and_saveexec_b64 s[16:17], vcc
	s_cbranch_execz .LBB0_1376
	s_add_u32 s14, s30, 0x40200
	s_addc_u32 s15, s31, 0
	s_mov_b32 s29, 1
	s_branch .LBB0_1369
